# v20 + packed f32 ops in the attention MFMA loops split into scalar pairs (asm guide 7.5)
# baseline (speedup 1.0000x reference)
.LBB0_457:
	s_and_b32 s12, s12, 0x3fffffc0
	v_and_b32_e32 v51, 63, v202
	s_lshr_b32 s13, s28, 6
	s_lshl_b32 s12, s12, 2
	s_or_b32 s13, s13, 3
	s_add_i32 s12, s12, 0
	v_lshlrev_b32_e32 v50, 8, v50
	v_and_b32_e32 v53, 0x70, v202
	v_lshlrev_b32_e32 v54, 4, v51
	s_min_u32 s29, s13, 63
	s_add_i32 s14, s12, 0x10000
	v_bitop3_b32 v53, v170, v50, v53 bitop3:0xde
	v_lshlrev_b32_e32 v50, 3, v51
	v_and_b32_e32 v54, 0xc0, v54
	v_lshlrev_b32_e32 v55, 1, v51
	v_and_or_b32 v54, v50, 24, v54
	v_and_b32_e32 v55, 32, v55
	v_and_b32_e32 v50, 0x100, v50
	s_cmp_lg_u32 0, -1
	v_or3_b32 v50, v54, v55, v50
	s_cselect_b32 s12, 0, 0
	v_add_u32_e32 v203, s12, v50
	v_and_b32_sdwa v50, v169, v198 dst_sel:DWORD dst_unused:UNUSED_PAD src0_sel:WORD_0 src1_sel:DWORD
	v_cmp_eq_u32_e32 vcc, 0, v50
	v_max_f32_e32 v50, v19, v19
	v_max_f32_e32 v54, v18, v18
	v_max_f32_e32 v50, v54, v50
	v_max3_f32 v50, v50, v20, v21
	v_max3_f32 v50, v50, v22, v23
	v_max3_f32 v50, v50, v24, v25
	v_max3_f32 v50, v50, v26, v27
	v_max3_f32 v50, v50, v28, v29
	v_max3_f32 v50, v50, v30, v31
	v_max3_f32 v50, v50, v32, v33
	v_max3_f32 v50, v50, v2, v3
	v_max3_f32 v50, v50, v4, v5
	v_max3_f32 v50, v50, v6, v7
	v_max3_f32 v50, v50, v8, v9
	v_max3_f32 v50, v50, v10, v11
	v_max3_f32 v50, v50, v12, v13
	v_max3_f32 v50, v50, v14, v15
	v_max3_f32 v50, v50, v16, v17
	s_add_i32 s30, s21, 0xc000001f
	v_mov_b32_e32 v54, v50
	s_cmp_lg_u32 s28, 0
	s_nop 0
	v_permlane32_swap_b32_e32 v50, v54
	s_cselect_b64 s[12:13], -1, 0
	v_max_f32_e32 v54, v54, v54
	v_max_f32_e32 v50, v50, v50
	v_max_f32_e32 v50, v50, v54
	s_and_b64 vcc, s[12:13], vcc
	v_cndmask_b32_e32 v50, v50, v189, vcc
	v_add_f32_e32 v54, 0x7149f2ca, v50
	v_mul_f32_e32 v54, 0x3db504f3, v54
	v_max_f32_e32 v50, 0xf149f2ca, v50
	v_cmp_ge_f32_e64 s[12:13], s76, v54
	v_sub_f32_e32 v54, 0xf149f2ca, v50
	v_mul_f32_e32 v54, 0x3e0293ee, v54
	s_cmp_eq_u64 s[12:13], exec
	v_exp_f32_e32 v54, v54
	s_cselect_b64 s[12:13], -1, 0
	v_cndmask_b32_e64 v213, v50, v199, s[12:13]
	v_mul_f32_e32 v50, 0xbe0293ee, v213
	v_cndmask_b32_e32 v50, v50, v189, vcc
	v_cndmask_b32_e64 v212, v54, 1.0, s[12:13]
	v_mov_b32_e32 v54, v50
	v_fmamk_f32 v18, v18, 0x3e0293ee, v50
	v_fmamk_f32 v19, v19, 0x3e0293ee, v50
	v_fmamk_f32 v20, v20, 0x3e0293ee, v50
	v_fmamk_f32 v21, v21, 0x3e0293ee, v50
	v_fmamk_f32 v22, v22, 0x3e0293ee, v50
	v_fmamk_f32 v23, v23, 0x3e0293ee, v50
	v_fmamk_f32 v24, v24, 0x3e0293ee, v50
	v_fmamk_f32 v25, v25, 0x3e0293ee, v50
	v_fmamk_f32 v26, v26, 0x3e0293ee, v50
	v_fmamk_f32 v27, v27, 0x3e0293ee, v50
	v_fmamk_f32 v28, v28, 0x3e0293ee, v50
	v_fmamk_f32 v29, v29, 0x3e0293ee, v50
	v_fmamk_f32 v30, v30, 0x3e0293ee, v50
	v_fmamk_f32 v31, v31, 0x3e0293ee, v50
	v_fmamk_f32 v32, v32, 0x3e0293ee, v50
	v_fmac_f32_e32 v54, 0x3e0293ee, v33
	v_lshl_add_u32 v205, v201, 2, s14
	v_lshl_add_u32 v204, v52, 2, s14
	s_add_i32 s14, s21, 0xffffff45
	v_fma_f32 v158, v2, s72, v50
	v_fma_f32 v159, v3, s72, v50
	v_exp_f32_e32 v228, v18
	v_exp_f32_e32 v230, v19
	v_exp_f32_e32 v226, v20
	v_exp_f32_e32 v229, v21
	v_exp_f32_e32 v225, v22
	v_exp_f32_e32 v227, v23
	v_exp_f32_e32 v223, v24
	v_exp_f32_e32 v224, v25
	v_exp_f32_e32 v220, v26
	v_exp_f32_e32 v222, v27
	v_exp_f32_e32 v219, v28
	v_exp_f32_e32 v221, v29
	v_exp_f32_e32 v184, v30
	v_exp_f32_e32 v218, v31
	v_exp_f32_e32 v183, v32
	v_exp_f32_e32 v185, v54
	v_add_u32_e32 v206, 0, v53
	v_add_u32_e32 v2, s14, v201
	s_waitcnt vmcnt(0)
	s_waitcnt vmcnt(3)
	ds_write_b128 v173, v[34:37] offset:16384
	s_waitcnt vmcnt(2)
	ds_write_b128 v209, v[38:41] offset:16384
	s_waitcnt vmcnt(1)
	ds_write_b128 v206, v[42:45] offset:49152
	s_waitcnt vmcnt(0)
	ds_write_b128 v206, v[46:49] offset:57344
	v_sub_u32_e32 v214, v2, v52
	v_and_b32_e32 v2, 15, v202
	v_mov_b32_e32 v34, v167
	v_mov_b32_e32 v35, v167
	v_mov_b32_e32 v48, v167
	v_mov_b32_e32 v49, v167
	v_fma_f32 v148, v16, s72, v50
	v_fma_f32 v149, v17, s72, v50
	v_fma_f32 v154, v14, s72, v50
	v_fma_f32 v155, v15, s72, v50
	v_fma_f32 v160, v12, s72, v50
	v_fma_f32 v161, v13, s72, v50
	v_fma_f32 v146, v10, s72, v50
	v_fma_f32 v147, v11, s72, v50
	v_fma_f32 v150, v8, s72, v50
	v_fma_f32 v151, v9, s72, v50
	v_fma_f32 v152, v6, s72, v50
	v_fma_f32 v153, v7, s72, v50
	v_fma_f32 v156, v4, s72, v50
	v_fma_f32 v157, v5, s72, v50
	v_cmp_gt_u32_e64 s[12:13], 32, v51
	v_lshlrev_b32_e32 v166, 4, v2
	v_mov_b32_e32 v36, v167
	v_mov_b32_e32 v37, v167
	v_mov_b32_e32 v38, v167
	v_mov_b32_e32 v39, v167
	v_mov_b32_e32 v40, v167
	v_mov_b32_e32 v41, v167
	v_mov_b32_e32 v42, v167
	v_mov_b32_e32 v43, v167
	v_mov_b32_e32 v44, v167
	v_mov_b32_e32 v45, v167
	v_mov_b32_e32 v46, v167
	v_mov_b32_e32 v47, v167
	v_mov_b64_e32 v[64:65], v[48:49]
	v_mov_b64_e32 v[18:19], v[34:35]
	v_mov_b64_e32 v[2:3], v[34:35]
	s_mov_b32 s34, 2
	v_lshl_add_u64 v[178:179], s[22:23], 0, v[174:175]
	v_lshl_add_u64 v[180:181], s[16:17], 0, v[174:175]
	v_mov_b32_e32 v207, 0
	s_movk_i32 s22, 0xbf
	v_mov_b64_e32 v[62:63], v[46:47]
	v_mov_b64_e32 v[60:61], v[44:45]
	v_mov_b64_e32 v[58:59], v[42:43]
	v_mov_b64_e32 v[56:57], v[40:41]
	v_mov_b64_e32 v[54:55], v[38:39]
	v_mov_b64_e32 v[52:53], v[36:37]
	v_mov_b64_e32 v[50:51], v[34:35]
	v_mov_b64_e32 v[20:21], v[36:37]
	v_mov_b64_e32 v[22:23], v[38:39]
	v_mov_b64_e32 v[24:25], v[40:41]
	v_mov_b64_e32 v[26:27], v[42:43]
	v_mov_b64_e32 v[28:29], v[44:45]
	v_mov_b64_e32 v[30:31], v[46:47]
	v_mov_b64_e32 v[32:33], v[48:49]
	v_mov_b64_e32 v[4:5], v[36:37]
	v_mov_b64_e32 v[6:7], v[38:39]
	v_mov_b64_e32 v[8:9], v[40:41]
	v_mov_b64_e32 v[10:11], v[42:43]
	v_mov_b64_e32 v[12:13], v[44:45]
	v_mov_b64_e32 v[14:15], v[46:47]
	v_mov_b64_e32 v[16:17], v[48:49]
	s_waitcnt lgkmcnt(0)
	s_barrier

.LBB0_460:
	s_cmp_lt_u32 s14, s28
	s_cselect_b64 s[16:17], -1, 0
	s_lshr_b32 s14, s14, 8
	s_lshl_b32 s14, 1, s14
	v_and_b32_sdwa v146, s14, v169 dst_sel:DWORD dst_unused:UNUSED_PAD src0_sel:DWORD src1_sel:WORD_0
	v_cmp_eq_u32_e32 vcc, 0, v146
	v_max_f32_e32 v146, v83, v83
	v_max_f32_e32 v147, v82, v82
	v_max_f32_e32 v146, v147, v146
	v_max3_f32 v146, v146, v84, v85
	v_max3_f32 v146, v146, v86, v87
	v_max3_f32 v146, v146, v88, v89
	v_max3_f32 v146, v146, v90, v91
	v_max3_f32 v146, v146, v92, v93
	v_max3_f32 v146, v146, v94, v95
	v_max3_f32 v146, v146, v96, v97
	v_max3_f32 v146, v146, v66, v67
	v_max3_f32 v146, v146, v68, v69
	v_max3_f32 v146, v146, v70, v71
	v_max3_f32 v146, v146, v72, v73
	v_max3_f32 v146, v146, v74, v75
	v_max3_f32 v146, v146, v76, v77
	v_max3_f32 v146, v146, v78, v79
	v_max3_f32 v146, v146, v80, v81
	v_mov_b32_e32 v147, v146
	s_nop 1
	v_permlane32_swap_b32_e32 v146, v147
	v_max_f32_e32 v147, v147, v147
	v_max_f32_e32 v146, v146, v146
	v_max_f32_e32 v146, v146, v147
	s_and_b64 s[14:15], s[16:17], vcc
	v_cndmask_b32_e64 v146, v146, v189, s[14:15]
	v_max_f32_e32 v148, v213, v213
	v_sub_f32_e32 v147, v146, v213
	v_max_f32_e32 v146, v148, v146
	v_sub_f32_e32 v148, v213, v146
	v_mul_f32_e32 v148, 0x3e0293ee, v148
	v_mul_f32_e32 v147, 0x3db504f3, v147
	v_exp_f32_e32 v148, v148
	v_cmp_ge_f32_e32 vcc, s76, v147
	s_cmp_eq_u64 vcc, exec
	s_cselect_b64 s[16:17], -1, 0
	s_barrier
	s_waitcnt vmcnt(0)
	v_cndmask_b32_e64 v217, v148, 1.0, s[16:17]
	v_cmp_gt_f32_e32 vcc, 1.0, v217
	s_waitcnt vmcnt(3)
	ds_write_b128 v173, v[130:133]
	s_waitcnt vmcnt(2)
	ds_write_b128 v209, v[134:137]
	s_waitcnt vmcnt(1)
	ds_write_b128 v206, v[138:141] offset:32768
	s_waitcnt vmcnt(0)
	ds_write_b128 v206, v[142:145] offset:40960
	s_cbranch_vccz .LBB0_464
	s_and_saveexec_b64 s[18:19], s[12:13]
	ds_write_b32 v205, v217 offset:128
	s_or_b64 exec, exec, s[18:19]
	s_waitcnt lgkmcnt(0)
	ds_read_b128 v[148:151], v204 offset:224
	ds_read_b128 v[152:155], v204 offset:192
	ds_read_b128 v[156:159], v204 offset:160
	ds_read_b128 v[218:221], v204 offset:128
	s_waitcnt lgkmcnt(3)
	v_mul_f32 v48, v48, v150
	v_mul_f32 v49, v49, v151
	s_waitcnt lgkmcnt(2)
	v_mul_f32 v44, v44, v154
	v_mul_f32 v45, v45, v155
	s_waitcnt lgkmcnt(1)
	v_mul_f32 v40, v40, v158
	v_mul_f32 v41, v41, v159
	s_waitcnt lgkmcnt(0)
	v_mul_f32 v36, v36, v220
	v_mul_f32 v37, v37, v221
	v_mul_f32 v46, v46, v148
	v_mul_f32 v47, v47, v149
	v_mul_f32 v42, v42, v152
	v_mul_f32 v43, v43, v153
	v_mul_f32 v38, v38, v156
	v_mul_f32 v39, v39, v157
	v_mul_f32 v34, v34, v218
	v_mul_f32 v35, v35, v219
	v_mul_f32 v64, v64, v150
	v_mul_f32 v65, v65, v151
	v_mul_f32 v60, v60, v154
	v_mul_f32 v61, v61, v155
	v_mul_f32 v56, v56, v158
	v_mul_f32 v57, v57, v159
	v_mul_f32 v52, v52, v220
	v_mul_f32 v53, v53, v221
	v_mul_f32 v62, v62, v148
	v_mul_f32 v63, v63, v149
	v_mul_f32 v58, v58, v152
	v_mul_f32 v59, v59, v153
	v_mul_f32 v54, v54, v156
	v_mul_f32 v55, v55, v157
	v_mul_f32 v50, v50, v218
	v_mul_f32 v51, v51, v219
	v_mul_f32 v32, v32, v150
	v_mul_f32 v33, v33, v151
	v_mul_f32 v28, v28, v154
	v_mul_f32 v29, v29, v155
	v_mul_f32 v24, v24, v158
	v_mul_f32 v25, v25, v159
	v_mul_f32 v20, v20, v220
	v_mul_f32 v21, v21, v221
	v_mul_f32 v30, v30, v148
	v_mul_f32 v31, v31, v149
	v_mul_f32 v26, v26, v152
	v_mul_f32 v27, v27, v153
	v_mul_f32 v22, v22, v156
	v_mul_f32 v23, v23, v157
	v_mul_f32 v18, v18, v218
	v_mul_f32 v19, v19, v219
	v_mul_f32 v16, v16, v150
	v_mul_f32 v17, v17, v151
	v_mul_f32 v12, v12, v154
	v_mul_f32 v13, v13, v155
	v_mul_f32 v8, v8, v158
	v_mul_f32 v9, v9, v159
	v_mul_f32 v4, v4, v220
	v_mul_f32 v5, v5, v221
	v_mul_f32 v14, v14, v148
	v_mul_f32 v15, v15, v149
	v_mul_f32 v10, v10, v152
	v_mul_f32 v11, v11, v153
	v_mul_f32 v6, v6, v156
	v_mul_f32 v7, v7, v157
	v_mul_f32 v2, v2, v218
	v_mul_f32 v3, v3, v219

.LBB0_470:
	s_waitcnt vmcnt(3)
	v_max_f32_e32 v130, v213, v213
	v_max_f32_e32 v130, v130, v146
	v_sub_f32_e32 v131, v213, v130
	v_mul_f32_e32 v131, 0x3e0293ee, v131
	v_exp_f32_e32 v131, v131
	s_nop 0
	v_cndmask_b32_e64 v182, v131, 1.0, s[16:17]
	v_cmp_gt_f32_e32 vcc, 1.0, v182
	s_cbranch_vccz .LBB0_474
	s_and_saveexec_b64 s[18:19], s[12:13]
	ds_write_b32 v205, v182 offset:128
	s_or_b64 exec, exec, s[18:19]
	s_waitcnt lgkmcnt(0)
	s_waitcnt vmcnt(2)
	ds_read_b128 v[132:135], v204 offset:224
	s_waitcnt vmcnt(1)
	ds_read_b128 v[136:139], v204 offset:192
	s_waitcnt vmcnt(0)
	ds_read_b128 v[140:143], v204 offset:160
	ds_read_b128 v[144:147], v204 offset:128
	s_waitcnt lgkmcnt(3)
	v_mul_f32 v48, v48, v134
	v_mul_f32 v49, v49, v135
	s_waitcnt lgkmcnt(2)
	v_mul_f32 v44, v44, v138
	v_mul_f32 v45, v45, v139
	s_waitcnt lgkmcnt(1)
	v_mul_f32 v40, v40, v142
	v_mul_f32 v41, v41, v143
	s_waitcnt lgkmcnt(0)
	v_mul_f32 v36, v36, v146
	v_mul_f32 v37, v37, v147
	v_mul_f32 v46, v46, v132
	v_mul_f32 v47, v47, v133
	v_mul_f32 v42, v42, v136
	v_mul_f32 v43, v43, v137
	v_mul_f32 v38, v38, v140
	v_mul_f32 v39, v39, v141
	v_mul_f32 v34, v34, v144
	v_mul_f32 v35, v35, v145
	v_mul_f32 v64, v64, v134
	v_mul_f32 v65, v65, v135
	v_mul_f32 v60, v60, v138
	v_mul_f32 v61, v61, v139
	v_mul_f32 v56, v56, v142
	v_mul_f32 v57, v57, v143
	v_mul_f32 v52, v52, v146
	v_mul_f32 v53, v53, v147
	v_mul_f32 v62, v62, v132
	v_mul_f32 v63, v63, v133
	v_mul_f32 v58, v58, v136
	v_mul_f32 v59, v59, v137
	v_mul_f32 v54, v54, v140
	v_mul_f32 v55, v55, v141
	v_mul_f32 v50, v50, v144
	v_mul_f32 v51, v51, v145
	v_mul_f32 v32, v32, v134
	v_mul_f32 v33, v33, v135
	v_mul_f32 v28, v28, v138
	v_mul_f32 v29, v29, v139
	v_mul_f32 v24, v24, v142
	v_mul_f32 v25, v25, v143
	v_mul_f32 v20, v20, v146
	v_mul_f32 v21, v21, v147
	v_mul_f32 v30, v30, v132
	v_mul_f32 v31, v31, v133
	v_mul_f32 v26, v26, v136
	v_mul_f32 v27, v27, v137
	v_mul_f32 v22, v22, v140
	v_mul_f32 v23, v23, v141
	v_mul_f32 v18, v18, v144
	v_mul_f32 v19, v19, v145
	v_mul_f32 v16, v16, v134
	v_mul_f32 v17, v17, v135
	v_mul_f32 v12, v12, v138
	v_mul_f32 v13, v13, v139
	v_mul_f32 v8, v8, v142
	v_mul_f32 v9, v9, v143
	v_mul_f32 v4, v4, v146
	v_mul_f32 v5, v5, v147
	v_mul_f32 v14, v14, v132
	v_mul_f32 v15, v15, v133
	v_mul_f32 v10, v10, v136
	v_mul_f32 v11, v11, v137
	v_mul_f32 v6, v6, v140
	v_mul_f32 v7, v7, v141
	v_mul_f32 v2, v2, v144
	v_mul_f32 v3, v3, v145
.LBB0_474:
	v_cndmask_b32_e64 v213, v130, v213, s[16:17]
	v_mul_f32_e32 v130, 0xbe0293ee, v213
	v_cndmask_b32_e64 v130, v130, v189, s[14:15]
	v_mov_b32_e32 v131, v130
	v_fmamk_f32 v82, v82, 0x3e0293ee, v130
	v_fmamk_f32 v83, v83, 0x3e0293ee, v130
	v_fmamk_f32 v84, v84, 0x3e0293ee, v130
	v_fmamk_f32 v85, v85, 0x3e0293ee, v130
	v_fmamk_f32 v86, v86, 0x3e0293ee, v130
	v_fmamk_f32 v87, v87, 0x3e0293ee, v130
	v_fmamk_f32 v88, v88, 0x3e0293ee, v130
	v_fmamk_f32 v89, v89, 0x3e0293ee, v130
	v_fmamk_f32 v90, v90, 0x3e0293ee, v130
	v_fmamk_f32 v91, v91, 0x3e0293ee, v130
	v_fmamk_f32 v92, v92, 0x3e0293ee, v130
	v_fmamk_f32 v93, v93, 0x3e0293ee, v130
	v_fmamk_f32 v94, v94, 0x3e0293ee, v130
	v_fmamk_f32 v95, v95, 0x3e0293ee, v130
	v_fmamk_f32 v96, v96, 0x3e0293ee, v130
	v_fmac_f32_e32 v131, 0x3e0293ee, v97
	v_exp_f32_e32 v228, v82
	v_exp_f32_e32 v230, v83
	v_exp_f32_e32 v226, v84
	v_exp_f32_e32 v229, v85
	v_exp_f32_e32 v225, v86
	v_exp_f32_e32 v227, v87
	v_exp_f32_e32 v223, v88
	v_exp_f32_e32 v224, v89
	v_exp_f32_e32 v220, v90
	v_exp_f32_e32 v222, v91
	v_exp_f32_e32 v219, v92
	v_exp_f32_e32 v221, v93
	v_exp_f32_e32 v184, v94
	v_exp_f32_e32 v218, v95
	v_exp_f32_e32 v183, v96
	v_exp_f32_e32 v185, v131
	v_fma_f32 v158, v66, s72, v130
	v_fma_f32 v159, v67, s72, v130
	v_add_f32_e32 v66, v215, v216
	v_fmac_f32_e32 v66, v212, v207
	v_add_f32_e32 v207, v231, v232
	s_add_i32 s34, s34, 2
	s_addk_i32 s22, 0x80
	v_fma_f32 v156, v68, s72, v130
	v_fma_f32 v157, v69, s72, v130
	v_fma_f32 v152, v70, s72, v130
	v_fma_f32 v153, v71, s72, v130
	v_fma_f32 v150, v72, s72, v130
	v_fma_f32 v151, v73, s72, v130
	v_fma_f32 v146, v74, s72, v130
	v_fma_f32 v147, v75, s72, v130
	v_fma_f32 v160, v76, s72, v130
	v_fma_f32 v161, v77, s72, v130
	v_fma_f32 v154, v78, s72, v130
	v_fma_f32 v155, v79, s72, v130
	v_fma_f32 v148, v80, s72, v130
	v_fma_f32 v149, v81, s72, v130
	v_fmac_f32_e32 v207, v66, v217
	v_add_u32_e32 v214, 0xffffff80, v214
	v_lshl_add_u64 v[178:179], v[178:179], 0, s[78:79]
	s_cmp_le_u32 s34, s29
	v_lshl_add_u64 v[180:181], v[180:181], 0, s[78:79]
	s_waitcnt lgkmcnt(0)
	s_barrier
	s_cbranch_scc0 .LBB0_476
	v_mov_b32_e32 v212, v182
	s_branch .LBB0_458

.LBB0_478:
	v_max_f32_e32 v148, v83, v83
	v_max_f32_e32 v149, v82, v82
	v_max_f32_e32 v148, v149, v148
	v_max3_f32 v148, v148, v84, v85
	v_max3_f32 v148, v148, v86, v87
	v_max3_f32 v148, v148, v88, v89
	v_max3_f32 v148, v148, v90, v91
	v_max3_f32 v148, v148, v92, v93
	v_max3_f32 v148, v148, v94, v95
	v_max3_f32 v148, v148, v96, v97
	v_max3_f32 v148, v148, v66, v67
	v_max3_f32 v148, v148, v68, v69
	v_max3_f32 v148, v148, v70, v71
	v_max3_f32 v148, v148, v72, v73
	v_max3_f32 v148, v148, v74, v75
	v_max3_f32 v148, v148, v76, v77
	v_max3_f32 v148, v148, v78, v79
	v_max3_f32 v148, v148, v80, v81
	v_mov_b32_e32 v149, v148
	s_nop 1
	v_permlane32_swap_b32_e32 v148, v149
	v_max_f32_e32 v149, v149, v149
	v_max_f32_e32 v148, v148, v148
	v_max_f32_e32 v148, v148, v149
	v_sub_f32_e32 v149, v148, v213
	v_mul_f32_e32 v150, 0x3db504f3, v149
	v_max_f32_e32 v149, v213, v213
	v_max_f32_e32 v149, v149, v148
	v_sub_f32_e32 v148, v213, v149
	v_mul_f32_e32 v148, 0x3e0293ee, v148
	v_exp_f32_e32 v148, v148
	v_cmp_ge_f32_e32 vcc, s76, v150
	s_cmp_eq_u64 vcc, exec
	s_cselect_b64 s[14:15], -1, 0
	v_cndmask_b32_e64 v148, v148, 1.0, s[14:15]
	v_cmp_gt_f32_e32 vcc, 1.0, v148
	s_barrier
	s_cbranch_vccz .LBB0_482
	s_and_saveexec_b64 s[18:19], s[12:13]
	ds_write_b32 v205, v148 offset:128
	s_or_b64 exec, exec, s[18:19]
	s_waitcnt lgkmcnt(0)
	ds_read_b128 v[150:153], v204 offset:224
	ds_read_b128 v[154:157], v204 offset:192
	ds_read_b128 v[158:161], v204 offset:160
	ds_read_b128 v[168:171], v204 offset:128
	s_waitcnt lgkmcnt(3)
	v_mul_f32 v48, v48, v152
	v_mul_f32 v49, v49, v153
	s_waitcnt lgkmcnt(2)
	v_mul_f32 v44, v44, v156
	v_mul_f32 v45, v45, v157
	s_waitcnt lgkmcnt(1)
	v_mul_f32 v40, v40, v160
	v_mul_f32 v41, v41, v161
	s_waitcnt lgkmcnt(0)
	v_mul_f32 v36, v36, v170
	v_mul_f32 v37, v37, v171
	v_mul_f32 v46, v46, v150
	v_mul_f32 v47, v47, v151
	v_mul_f32 v42, v42, v154
	v_mul_f32 v43, v43, v155
	v_mul_f32 v38, v38, v158
	v_mul_f32 v39, v39, v159
	v_mul_f32 v34, v34, v168
	v_mul_f32 v35, v35, v169
	v_mul_f32 v64, v64, v152
	v_mul_f32 v65, v65, v153
	v_mul_f32 v60, v60, v156
	v_mul_f32 v61, v61, v157
	v_mul_f32 v56, v56, v160
	v_mul_f32 v57, v57, v161
	v_mul_f32 v52, v52, v170
	v_mul_f32 v53, v53, v171
	v_mul_f32 v62, v62, v150
	v_mul_f32 v63, v63, v151
	v_mul_f32 v58, v58, v154
	v_mul_f32 v59, v59, v155
	v_mul_f32 v54, v54, v158
	v_mul_f32 v55, v55, v159
	v_mul_f32 v50, v50, v168
	v_mul_f32 v51, v51, v169
	v_mul_f32 v32, v32, v152
	v_mul_f32 v33, v33, v153
	v_mul_f32 v28, v28, v156
	v_mul_f32 v29, v29, v157
	v_mul_f32 v24, v24, v160
	v_mul_f32 v25, v25, v161
	v_mul_f32 v20, v20, v170
	v_mul_f32 v21, v21, v171
	v_mul_f32 v30, v30, v150
	v_mul_f32 v31, v31, v151
	v_mul_f32 v26, v26, v154
	v_mul_f32 v27, v27, v155
	v_mul_f32 v22, v22, v158
	v_mul_f32 v23, v23, v159
	v_mul_f32 v18, v18, v168
	v_mul_f32 v19, v19, v169
	v_mul_f32 v16, v16, v152
	v_mul_f32 v17, v17, v153
	v_mul_f32 v12, v12, v156
	v_mul_f32 v13, v13, v157
	v_mul_f32 v8, v8, v160
	v_mul_f32 v9, v9, v161
	v_mul_f32 v4, v4, v170
	v_mul_f32 v5, v5, v171
	v_mul_f32 v14, v14, v150
	v_mul_f32 v15, v15, v151
	v_mul_f32 v10, v10, v154
	v_mul_f32 v11, v11, v155
	v_mul_f32 v6, v6, v158
	v_mul_f32 v7, v7, v159
	v_mul_f32 v2, v2, v168
	v_mul_f32 v3, v3, v169

.LBB0_622:
	v_max_f32_e32 v35, 0xf149f2ca, v51
	v_cndmask_b32_e64 v194, v35, v177, s[0:1]
	v_mul_f32_e32 v34, 0xbe0293ee, v194
	v_fmamk_f32 v18, v18, 0x3e0293ee, v34
	v_exp_f32_e32 v213, v18
	v_sub_f32_e32 v18, 0xf149f2ca, v35
	v_mul_f32_e32 v18, 0x3e0293ee, v18
	v_exp_f32_e32 v18, v18
	v_and_b32_e32 v179, 63, v172
	v_fmamk_f32 v19, v19, 0x3e0293ee, v34
	v_fmamk_f32 v20, v20, 0x3e0293ee, v34
	v_fmamk_f32 v21, v21, 0x3e0293ee, v34
	v_fmamk_f32 v22, v22, 0x3e0293ee, v34
	v_fmamk_f32 v23, v23, 0x3e0293ee, v34
	v_fmamk_f32 v24, v24, 0x3e0293ee, v34
	v_fmamk_f32 v25, v25, 0x3e0293ee, v34
	v_fmamk_f32 v26, v26, 0x3e0293ee, v34
	v_fmamk_f32 v27, v27, 0x3e0293ee, v34
	v_fmamk_f32 v28, v28, 0x3e0293ee, v34
	v_fmamk_f32 v29, v29, 0x3e0293ee, v34
	v_fmamk_f32 v30, v30, 0x3e0293ee, v34
	v_fmamk_f32 v31, v31, 0x3e0293ee, v34
	v_fmamk_f32 v32, v32, 0x3e0293ee, v34
	v_fmamk_f32 v33, v33, 0x3e0293ee, v34
	v_cndmask_b32_e64 v193, v18, 1.0, s[0:1]
	v_fma_f32 v170, v2, s8, v34
	v_fma_f32 v171, v3, s8, v34
	s_and_b32 s0, s69, 0x3fffffc0
	v_lshlrev_b32_e32 v3, 4, v179
	v_exp_f32_e32 v215, v19
	v_exp_f32_e32 v211, v20
	v_exp_f32_e32 v214, v21
	v_exp_f32_e32 v210, v22
	v_exp_f32_e32 v212, v23
	v_exp_f32_e32 v208, v24
	v_exp_f32_e32 v209, v25
	v_exp_f32_e32 v203, v26
	v_exp_f32_e32 v206, v27
	v_exp_f32_e32 v201, v28
	v_exp_f32_e32 v204, v29
	v_exp_f32_e32 v200, v30
	v_exp_f32_e32 v207, v31
	v_exp_f32_e32 v202, v32
	v_exp_f32_e32 v205, v33
	v_fma_f32 v160, v4, s8, v34
	v_fma_f32 v161, v5, s8, v34
	s_lshl_b32 s0, s0, 2
	v_lshlrev_b32_e32 v2, 3, v179
	v_and_b32_e32 v3, 0xc0, v3
	v_lshlrev_b32_e32 v4, 1, v179
	s_add_i32 s0, s0, 0
	v_and_or_b32 v3, v2, 24, v3
	v_and_b32_e32 v4, 32, v4
	v_and_b32_e32 v2, 0x100, v2
	s_add_i32 s69, s0, 0x10000
	v_or3_b32 v2, v3, v4, v2
	v_fma_f32 v148, v16, s8, v34
	v_fma_f32 v149, v17, s8, v34
	v_fma_f32 v150, v14, s8, v34
	v_fma_f32 v151, v15, s8, v34
	v_fma_f32 v152, v12, s8, v34
	v_fma_f32 v153, v13, s8, v34
	v_fma_f32 v154, v10, s8, v34
	v_fma_f32 v155, v11, s8, v34
	v_fma_f32 v156, v8, s8, v34
	v_fma_f32 v157, v9, s8, v34
	v_fma_f32 v158, v6, s8, v34
	v_fma_f32 v159, v7, s8, v34
	v_add_u32_e32 v182, s73, v2
	v_mov_b32_e32 v17, 0
	s_andn2_b64 vcc, exec, s[18:19]
	v_cmp_gt_u32_e64 s[0:1], 32, v179
	v_lshl_add_u32 v181, v174, 2, s69
	v_lshl_add_u32 v180, v52, 2, s69
	s_cbranch_vccnz .LBB0_642
	v_mov_b32_e32 v51, v163
	v_lshl_add_u64 v[168:169], s[2:3], 0, v[50:51]
	s_add_i32 s2, s68, 0xffffff45
	v_add_u32_e32 v2, s2, v174
	v_sub_u32_e32 v2, v2, v52
	v_mov_b32_e32 v186, 0
	v_mov_b32_e32 v165, v163
	v_lshl_add_u64 v[166:167], s[4:5], 0, v[50:51]
	s_mov_b32 s18, 2
	v_subrev_u32_e32 v195, s72, v2
	s_add_i32 s19, s72, 0x7f
	v_mov_b32_e32 v50, 0
	v_mov_b32_e32 v51, v186
	v_mov_b32_e32 v52, v186
	v_mov_b32_e32 v53, v186
	v_mov_b32_e32 v54, v186
	v_mov_b32_e32 v55, v186
	v_mov_b32_e32 v56, v186
	v_mov_b32_e32 v57, v186
	v_mov_b32_e32 v58, v186
	v_mov_b32_e32 v59, v186
	v_mov_b32_e32 v60, v186
	v_mov_b32_e32 v61, v186
	v_mov_b32_e32 v62, v186
	v_mov_b32_e32 v63, v186
	v_mov_b32_e32 v64, v186
	v_mov_b32_e32 v65, v186
	v_mov_b32_e32 v34, 0
	v_mov_b32_e32 v35, v186
	v_mov_b32_e32 v36, v186
	v_mov_b32_e32 v37, v186
	v_mov_b32_e32 v38, v186
	v_mov_b32_e32 v39, v186
	v_mov_b32_e32 v40, v186
	v_mov_b32_e32 v41, v186
	v_mov_b32_e32 v42, v186
	v_mov_b32_e32 v43, v186
	v_mov_b32_e32 v44, v186
	v_mov_b32_e32 v45, v186
	v_mov_b32_e32 v46, v186
	v_mov_b32_e32 v47, v186
	v_mov_b32_e32 v48, v186
	v_mov_b32_e32 v49, v186
	v_mov_b32_e32 v18, 0
	v_mov_b32_e32 v19, v186
	v_mov_b32_e32 v20, v186
	v_mov_b32_e32 v21, v186
	v_mov_b32_e32 v22, v186
	v_mov_b32_e32 v23, v186
	v_mov_b32_e32 v24, v186
	v_mov_b32_e32 v25, v186
	v_mov_b32_e32 v26, v186
	v_mov_b32_e32 v27, v186
	v_mov_b32_e32 v28, v186
	v_mov_b32_e32 v29, v186
	v_mov_b32_e32 v30, v186
	v_mov_b32_e32 v31, v186
	v_mov_b32_e32 v32, v186
	v_mov_b32_e32 v33, v186
	v_mov_b32_e32 v2, 0
	v_mov_b32_e32 v3, v186
	v_mov_b32_e32 v4, v186
	v_mov_b32_e32 v5, v186
	v_mov_b32_e32 v6, v186
	v_mov_b32_e32 v7, v186
	v_mov_b32_e32 v8, v186
	v_mov_b32_e32 v9, v186
	v_mov_b32_e32 v10, v186
	v_mov_b32_e32 v11, v186
	v_mov_b32_e32 v12, v186
	v_mov_b32_e32 v13, v186
	v_mov_b32_e32 v14, v186
	v_mov_b32_e32 v15, v186
	v_mov_b32_e32 v16, v186
	v_mov_b32_e32 v17, v186

.LBB0_626:
	v_max_f32_e32 v146, v83, v83
	v_max_f32_e32 v147, v82, v82
	v_max_f32_e32 v146, v147, v146
	v_max3_f32 v146, v146, v84, v85
	v_max3_f32 v146, v146, v86, v87
	v_max3_f32 v146, v146, v88, v89
	v_max3_f32 v146, v146, v90, v91
	v_max3_f32 v146, v146, v92, v93
	v_max3_f32 v146, v146, v94, v95
	v_max3_f32 v146, v146, v96, v97
	v_max3_f32 v146, v146, v66, v67
	v_max3_f32 v146, v146, v68, v69
	v_max3_f32 v146, v146, v70, v71
	v_max3_f32 v146, v146, v72, v73
	v_max3_f32 v146, v146, v74, v75
	v_max3_f32 v146, v146, v76, v77
	v_max3_f32 v146, v146, v78, v79
	v_max3_f32 v146, v146, v80, v81
	v_mov_b32_e32 v147, v146
	s_nop 1
	v_permlane32_swap_b32_e32 v146, v147
	v_max_f32_e32 v147, v147, v147
	v_max_f32_e32 v146, v146, v146
	v_max_f32_e32 v146, v146, v147
	v_max_f32_e32 v148, v194, v194
	v_sub_f32_e32 v147, v146, v194
	v_max_f32_e32 v146, v148, v146
	v_sub_f32_e32 v148, v194, v146
	v_mul_f32_e32 v148, 0x3e0293ee, v148
	v_mul_f32_e32 v147, 0x3db504f3, v147
	v_exp_f32_e32 v148, v148
	v_cmp_ge_f32_e32 vcc, s34, v147
	s_cmp_eq_u64 vcc, exec
	s_cselect_b64 s[2:3], -1, 0
	s_barrier
	s_waitcnt vmcnt(0)
	v_cndmask_b32_e64 v199, v148, 1.0, s[2:3]
	v_cmp_gt_f32_e32 vcc, 1.0, v199
	s_waitcnt vmcnt(3)
	ds_write_b128 v191, v[130:133]
	s_waitcnt vmcnt(2)
	ds_write_b128 v192, v[134:137]
	s_waitcnt vmcnt(1)
	ds_write_b128 v175, v[138:141] offset:32768
	s_waitcnt vmcnt(0)
	ds_write_b128 v175, v[142:145] offset:40960
	s_cbranch_vccz .LBB0_630
	s_and_saveexec_b64 s[4:5], s[0:1]
	ds_write_b32 v181, v199 offset:128
	s_or_b64 exec, exec, s[4:5]
	s_waitcnt lgkmcnt(0)
	ds_read_b128 v[148:151], v180 offset:224
	ds_read_b128 v[152:155], v180 offset:192
	ds_read_b128 v[156:159], v180 offset:160
	ds_read_b128 v[200:203], v180 offset:128
	s_waitcnt lgkmcnt(3)
	v_mul_f32 v64, v64, v150
	v_mul_f32 v65, v65, v151
	s_waitcnt lgkmcnt(2)
	v_mul_f32 v60, v60, v154
	v_mul_f32 v61, v61, v155
	s_waitcnt lgkmcnt(1)
	v_mul_f32 v56, v56, v158
	v_mul_f32 v57, v57, v159
	s_waitcnt lgkmcnt(0)
	v_mul_f32 v52, v52, v202
	v_mul_f32 v53, v53, v203
	v_mul_f32 v62, v62, v148
	v_mul_f32 v63, v63, v149
	v_mul_f32 v58, v58, v152
	v_mul_f32 v59, v59, v153
	v_mul_f32 v54, v54, v156
	v_mul_f32 v55, v55, v157
	v_mul_f32 v50, v50, v200
	v_mul_f32 v51, v51, v201
	v_mul_f32 v48, v48, v150
	v_mul_f32 v49, v49, v151
	v_mul_f32 v44, v44, v154
	v_mul_f32 v45, v45, v155
	v_mul_f32 v40, v40, v158
	v_mul_f32 v41, v41, v159
	v_mul_f32 v36, v36, v202
	v_mul_f32 v37, v37, v203
	v_mul_f32 v46, v46, v148
	v_mul_f32 v47, v47, v149
	v_mul_f32 v42, v42, v152
	v_mul_f32 v43, v43, v153
	v_mul_f32 v38, v38, v156
	v_mul_f32 v39, v39, v157
	v_mul_f32 v34, v34, v200
	v_mul_f32 v35, v35, v201
	v_mul_f32 v32, v32, v150
	v_mul_f32 v33, v33, v151
	v_mul_f32 v28, v28, v154
	v_mul_f32 v29, v29, v155
	v_mul_f32 v24, v24, v158
	v_mul_f32 v25, v25, v159
	v_mul_f32 v20, v20, v202
	v_mul_f32 v21, v21, v203
	v_mul_f32 v30, v30, v148
	v_mul_f32 v31, v31, v149
	v_mul_f32 v26, v26, v152
	v_mul_f32 v27, v27, v153
	v_mul_f32 v22, v22, v156
	v_mul_f32 v23, v23, v157
	v_mul_f32 v18, v18, v200
	v_mul_f32 v19, v19, v201
	v_mul_f32 v16, v16, v150
	v_mul_f32 v17, v17, v151
	v_mul_f32 v12, v12, v154
	v_mul_f32 v13, v13, v155
	v_mul_f32 v8, v8, v158
	v_mul_f32 v9, v9, v159
	v_mul_f32 v4, v4, v202
	v_mul_f32 v5, v5, v203
	v_mul_f32 v14, v14, v148
	v_mul_f32 v15, v15, v149
	v_mul_f32 v10, v10, v152
	v_mul_f32 v11, v11, v153
	v_mul_f32 v6, v6, v156
	v_mul_f32 v7, v7, v157
	v_mul_f32 v2, v2, v200
	v_mul_f32 v3, v3, v201

.LBB0_636:
	s_waitcnt vmcnt(3)
	v_max_f32_e32 v130, v170, v170
	v_max_f32_e32 v130, v130, v146
	v_sub_f32_e32 v131, v170, v130
	v_mul_f32_e32 v131, 0x3e0293ee, v131
	v_exp_f32_e32 v131, v131
	s_nop 0
	v_cndmask_b32_e64 v198, v131, 1.0, s[2:3]
	v_cmp_gt_f32_e32 vcc, 1.0, v198
	s_cbranch_vccz .LBB0_640
	s_and_saveexec_b64 s[4:5], s[0:1]
	ds_write_b32 v181, v198 offset:128
	s_or_b64 exec, exec, s[4:5]
	s_waitcnt lgkmcnt(0)
	s_waitcnt vmcnt(2)
	ds_read_b128 v[132:135], v180 offset:224
	s_waitcnt vmcnt(1)
	ds_read_b128 v[136:139], v180 offset:192
	s_waitcnt vmcnt(0)
	ds_read_b128 v[140:143], v180 offset:160
	ds_read_b128 v[144:147], v180 offset:128
	s_waitcnt lgkmcnt(3)
	v_mul_f32 v64, v64, v134
	v_mul_f32 v65, v65, v135
	s_waitcnt lgkmcnt(2)
	v_mul_f32 v60, v60, v138
	v_mul_f32 v61, v61, v139
	s_waitcnt lgkmcnt(1)
	v_mul_f32 v56, v56, v142
	v_mul_f32 v57, v57, v143
	s_waitcnt lgkmcnt(0)
	v_mul_f32 v52, v52, v146
	v_mul_f32 v53, v53, v147
	v_mul_f32 v62, v62, v132
	v_mul_f32 v63, v63, v133
	v_mul_f32 v58, v58, v136
	v_mul_f32 v59, v59, v137
	v_mul_f32 v54, v54, v140
	v_mul_f32 v55, v55, v141
	v_mul_f32 v50, v50, v144
	v_mul_f32 v51, v51, v145
	v_mul_f32 v48, v48, v134
	v_mul_f32 v49, v49, v135
	v_mul_f32 v44, v44, v138
	v_mul_f32 v45, v45, v139
	v_mul_f32 v40, v40, v142
	v_mul_f32 v41, v41, v143
	v_mul_f32 v36, v36, v146
	v_mul_f32 v37, v37, v147
	v_mul_f32 v46, v46, v132
	v_mul_f32 v47, v47, v133
	v_mul_f32 v42, v42, v136
	v_mul_f32 v43, v43, v137
	v_mul_f32 v38, v38, v140
	v_mul_f32 v39, v39, v141
	v_mul_f32 v34, v34, v144
	v_mul_f32 v35, v35, v145
	v_mul_f32 v32, v32, v134
	v_mul_f32 v33, v33, v135
	v_mul_f32 v28, v28, v138
	v_mul_f32 v29, v29, v139
	v_mul_f32 v24, v24, v142
	v_mul_f32 v25, v25, v143
	v_mul_f32 v20, v20, v146
	v_mul_f32 v21, v21, v147
	v_mul_f32 v30, v30, v132
	v_mul_f32 v31, v31, v133
	v_mul_f32 v26, v26, v136
	v_mul_f32 v27, v27, v137
	v_mul_f32 v22, v22, v140
	v_mul_f32 v23, v23, v141
	v_mul_f32 v18, v18, v144
	v_mul_f32 v19, v19, v145
	v_mul_f32 v16, v16, v134
	v_mul_f32 v17, v17, v135
	v_mul_f32 v12, v12, v138
	v_mul_f32 v13, v13, v139
	v_mul_f32 v8, v8, v142
	v_mul_f32 v9, v9, v143
	v_mul_f32 v4, v4, v146
	v_mul_f32 v5, v5, v147
	v_mul_f32 v14, v14, v132
	v_mul_f32 v15, v15, v133
	v_mul_f32 v10, v10, v136
	v_mul_f32 v11, v11, v137
	v_mul_f32 v6, v6, v140
	v_mul_f32 v7, v7, v141
	v_mul_f32 v2, v2, v144
	v_mul_f32 v3, v3, v145
.LBB0_640:
	v_cndmask_b32_e64 v194, v130, v170, s[2:3]
	v_mul_f32_e32 v130, 0xbe0293ee, v194
	v_mov_b32_e32 v131, v130
	v_fmamk_f32 v82, v82, 0x3e0293ee, v130
	v_fmamk_f32 v83, v83, 0x3e0293ee, v130
	v_fmamk_f32 v84, v84, 0x3e0293ee, v130
	v_fmamk_f32 v85, v85, 0x3e0293ee, v130
	v_fmamk_f32 v86, v86, 0x3e0293ee, v130
	v_fmamk_f32 v87, v87, 0x3e0293ee, v130
	v_fmamk_f32 v88, v88, 0x3e0293ee, v130
	v_fmamk_f32 v89, v89, 0x3e0293ee, v130
	v_fmamk_f32 v90, v90, 0x3e0293ee, v130
	v_fmamk_f32 v91, v91, 0x3e0293ee, v130
	v_fmamk_f32 v92, v92, 0x3e0293ee, v130
	v_fmamk_f32 v93, v93, 0x3e0293ee, v130
	v_fmamk_f32 v94, v94, 0x3e0293ee, v130
	v_fmamk_f32 v95, v95, 0x3e0293ee, v130
	v_fmamk_f32 v96, v96, 0x3e0293ee, v130
	v_fmac_f32_e32 v131, 0x3e0293ee, v97
	v_exp_f32_e32 v213, v82
	v_exp_f32_e32 v215, v83
	v_exp_f32_e32 v211, v84
	v_exp_f32_e32 v214, v85
	v_exp_f32_e32 v210, v86
	v_exp_f32_e32 v212, v87
	v_exp_f32_e32 v208, v88
	v_exp_f32_e32 v209, v89
	v_exp_f32_e32 v203, v90
	v_exp_f32_e32 v206, v91
	v_exp_f32_e32 v201, v92
	v_exp_f32_e32 v204, v93
	v_exp_f32_e32 v200, v94
	v_exp_f32_e32 v207, v95
	v_exp_f32_e32 v202, v96
	v_exp_f32_e32 v205, v131
	v_fma_f32 v170, v66, s8, v130
	v_fma_f32 v171, v67, s8, v130
	v_add_f32_e32 v66, v196, v197
	v_fmac_f32_e32 v66, v193, v186
	v_add_f32_e32 v186, v216, v217
	s_addk_i32 s19, 0x80
	s_add_i32 s18, s18, 2
	v_fma_f32 v148, v80, s8, v130
	v_fma_f32 v149, v81, s8, v130
	v_fma_f32 v150, v78, s8, v130
	v_fma_f32 v151, v79, s8, v130
	v_fma_f32 v152, v76, s8, v130
	v_fma_f32 v153, v77, s8, v130
	v_fma_f32 v154, v74, s8, v130
	v_fma_f32 v155, v75, s8, v130
	v_fma_f32 v156, v72, s8, v130
	v_fma_f32 v157, v73, s8, v130
	v_fma_f32 v158, v70, s8, v130
	v_fma_f32 v159, v71, s8, v130
	v_fma_f32 v160, v68, s8, v130
	v_fma_f32 v161, v69, s8, v130
	v_fmac_f32_e32 v186, v66, v199
	s_cmp_lt_i32 s18, s29
	v_add_u32_e32 v195, 0xffffff80, v195
	s_waitcnt lgkmcnt(0)
	s_barrier
	s_cbranch_scc0 .LBB0_643
	v_mov_b32_e32 v193, v198
	s_branch .LBB0_624

.LBB0_645:
	v_max_f32_e32 v149, v83, v83
	v_max_f32_e32 v150, v82, v82
	v_max_f32_e32 v149, v150, v149
	v_max3_f32 v149, v149, v84, v85
	v_max3_f32 v149, v149, v86, v87
	v_max3_f32 v149, v149, v88, v89
	v_max3_f32 v149, v149, v90, v91
	v_max3_f32 v149, v149, v92, v93
	v_max3_f32 v149, v149, v94, v95
	v_max3_f32 v149, v149, v96, v97
	v_max3_f32 v149, v149, v66, v67
	v_max3_f32 v149, v149, v68, v69
	v_max3_f32 v149, v149, v70, v71
	v_max3_f32 v149, v149, v72, v73
	v_max3_f32 v149, v149, v74, v75
	v_max3_f32 v149, v149, v76, v77
	v_max3_f32 v149, v149, v78, v79
	v_max3_f32 v149, v149, v80, v81
	v_mov_b32_e32 v150, v149
	s_nop 1
	v_permlane32_swap_b32_e32 v149, v150
	v_max_f32_e32 v150, v150, v150
	v_max_f32_e32 v149, v149, v149
	v_max_f32_e32 v149, v149, v150
	v_max_f32_e32 v151, v194, v194
	v_sub_f32_e32 v150, v149, v194
	v_max_f32_e32 v149, v151, v149
	v_sub_f32_e32 v151, v194, v149
	v_mul_f32_e32 v151, 0x3e0293ee, v151
	v_mul_f32_e32 v150, 0x3db504f3, v150
	v_exp_f32_e32 v151, v151
	v_cmp_ge_f32_e32 vcc, s34, v150
	s_cmp_eq_u64 vcc, exec
	s_cselect_b64 s[0:1], -1, 0
	v_cndmask_b32_e64 v150, v151, 1.0, s[0:1]
	v_cmp_gt_f32_e32 vcc, 1.0, v150
	s_barrier
	s_cbranch_vccz .LBB0_649
	v_cmp_gt_u32_e32 vcc, 32, v179
	s_and_saveexec_b64 s[18:19], vcc
	ds_write_b32 v181, v150 offset:128
	s_or_b64 exec, exec, s[18:19]
	s_waitcnt lgkmcnt(0)
	ds_read_b128 v[152:155], v180 offset:224
	ds_read_b128 v[156:159], v180 offset:192
	ds_read_b128 v[164:167], v180 offset:160
	ds_read_b128 v[168:171], v180 offset:128
	s_waitcnt lgkmcnt(3)
	v_mul_f32 v64, v64, v154
	v_mul_f32 v65, v65, v155
	s_waitcnt lgkmcnt(2)
	v_mul_f32 v60, v60, v158
	v_mul_f32 v61, v61, v159
	s_waitcnt lgkmcnt(1)
	v_mul_f32 v56, v56, v166
	v_mul_f32 v57, v57, v167
	s_waitcnt lgkmcnt(0)
	v_mul_f32 v52, v52, v170
	v_mul_f32 v53, v53, v171
	v_mul_f32 v62, v62, v152
	v_mul_f32 v63, v63, v153
	v_mul_f32 v58, v58, v156
	v_mul_f32 v59, v59, v157
	v_mul_f32 v54, v54, v164
	v_mul_f32 v55, v55, v165
	v_mul_f32 v50, v50, v168
	v_mul_f32 v51, v51, v169
	v_mul_f32 v48, v48, v154
	v_mul_f32 v49, v49, v155
	v_mul_f32 v44, v44, v158
	v_mul_f32 v45, v45, v159
	v_mul_f32 v40, v40, v166
	v_mul_f32 v41, v41, v167
	v_mul_f32 v36, v36, v170
	v_mul_f32 v37, v37, v171
	v_mul_f32 v46, v46, v152
	v_mul_f32 v47, v47, v153
	v_mul_f32 v42, v42, v156
	v_mul_f32 v43, v43, v157
	v_mul_f32 v38, v38, v164
	v_mul_f32 v39, v39, v165
	v_mul_f32 v34, v34, v168
	v_mul_f32 v35, v35, v169
	v_mul_f32 v32, v32, v154
	v_mul_f32 v33, v33, v155
	v_mul_f32 v28, v28, v158
	v_mul_f32 v29, v29, v159
	v_mul_f32 v24, v24, v166
	v_mul_f32 v25, v25, v167
	v_mul_f32 v20, v20, v170
	v_mul_f32 v21, v21, v171
	v_mul_f32 v30, v30, v152
	v_mul_f32 v31, v31, v153
	v_mul_f32 v26, v26, v156
	v_mul_f32 v27, v27, v157
	v_mul_f32 v22, v22, v164
	v_mul_f32 v23, v23, v165
	v_mul_f32 v18, v18, v168
	v_mul_f32 v19, v19, v169
	v_mul_f32 v16, v16, v154
	v_mul_f32 v17, v17, v155
	v_mul_f32 v12, v12, v158
	v_mul_f32 v13, v13, v159
	v_mul_f32 v8, v8, v166
	v_mul_f32 v9, v9, v167
	v_mul_f32 v4, v4, v170
	v_mul_f32 v5, v5, v171
	v_mul_f32 v14, v14, v152
	v_mul_f32 v15, v15, v153
	v_mul_f32 v10, v10, v156
	v_mul_f32 v11, v11, v157
	v_mul_f32 v6, v6, v164
	v_mul_f32 v7, v7, v165
	v_mul_f32 v2, v2, v168
	v_mul_f32 v3, v3, v169

.LBB0_789:
	v_max_f32_e32 v35, 0xf149f2ca, v35
	v_cndmask_b32_e64 v194, v35, v177, s[0:1]
	v_mul_f32_e32 v38, 0xbe0293ee, v194
	v_fmamk_f32 v18, v18, 0x3e0293ee, v38
	v_exp_f32_e32 v213, v18
	v_sub_f32_e32 v18, 0xf149f2ca, v35
	v_mul_f32_e32 v18, 0x3e0293ee, v18
	v_exp_f32_e32 v18, v18
	v_and_b32_e32 v183, 63, v179
	v_fmamk_f32 v19, v19, 0x3e0293ee, v38
	v_fmamk_f32 v20, v20, 0x3e0293ee, v38
	v_fmamk_f32 v21, v21, 0x3e0293ee, v38
	v_fmamk_f32 v22, v22, 0x3e0293ee, v38
	v_fmamk_f32 v23, v23, 0x3e0293ee, v38
	v_fmamk_f32 v24, v24, 0x3e0293ee, v38
	v_fmamk_f32 v25, v25, 0x3e0293ee, v38
	v_fmamk_f32 v26, v26, 0x3e0293ee, v38
	v_fmamk_f32 v27, v27, 0x3e0293ee, v38
	v_fmamk_f32 v28, v28, 0x3e0293ee, v38
	v_fmamk_f32 v29, v29, 0x3e0293ee, v38
	v_fmamk_f32 v30, v30, 0x3e0293ee, v38
	v_fmamk_f32 v31, v31, 0x3e0293ee, v38
	v_fmamk_f32 v32, v32, 0x3e0293ee, v38
	v_fmamk_f32 v33, v33, 0x3e0293ee, v38
	v_cndmask_b32_e64 v193, v18, 1.0, s[0:1]
	v_fma_f32 v174, v2, s8, v38
	v_fma_f32 v175, v3, s8, v38
	s_and_b32 s0, s76, 0x3fffffc0
	v_lshlrev_b32_e32 v3, 4, v183
	v_exp_f32_e32 v215, v19
	v_exp_f32_e32 v211, v20
	v_exp_f32_e32 v214, v21
	v_exp_f32_e32 v210, v22
	v_exp_f32_e32 v212, v23
	v_exp_f32_e32 v208, v24
	v_exp_f32_e32 v209, v25
	v_exp_f32_e32 v203, v26
	v_exp_f32_e32 v206, v27
	v_exp_f32_e32 v201, v28
	v_exp_f32_e32 v204, v29
	v_exp_f32_e32 v200, v30
	v_exp_f32_e32 v207, v31
	v_exp_f32_e32 v202, v32
	v_exp_f32_e32 v205, v33
	v_fma_f32 v160, v4, s8, v38
	v_fma_f32 v161, v5, s8, v38
	s_lshl_b32 s0, s0, 2
	v_lshlrev_b32_e32 v2, 3, v183
	v_and_b32_e32 v3, 0xc0, v3
	v_lshlrev_b32_e32 v4, 1, v183
	s_add_i32 s0, s0, 0
	v_and_or_b32 v3, v2, 24, v3
	v_and_b32_e32 v4, 32, v4
	v_and_b32_e32 v2, 0x100, v2
	s_add_i32 s76, s0, 0x10000
	v_or3_b32 v2, v3, v4, v2
	v_fma_f32 v148, v16, s8, v38
	v_fma_f32 v149, v17, s8, v38
	v_fma_f32 v150, v14, s8, v38
	v_fma_f32 v151, v15, s8, v38
	v_fma_f32 v152, v12, s8, v38
	v_fma_f32 v153, v13, s8, v38
	v_fma_f32 v154, v10, s8, v38
	v_fma_f32 v155, v11, s8, v38
	v_fma_f32 v156, v8, s8, v38
	v_fma_f32 v157, v9, s8, v38
	v_fma_f32 v158, v6, s8, v38
	v_fma_f32 v159, v7, s8, v38
	v_add_u32_e32 v186, s73, v2
	v_mov_b32_e32 v17, 0
	s_andn2_b64 vcc, exec, s[18:19]
	v_cmp_gt_u32_e64 s[0:1], 32, v183
	v_lshl_add_u32 v185, v181, 2, s76
	v_lshl_add_u32 v184, v36, 2, s76
	s_cbranch_vccnz .LBB0_809
	v_mov_b32_e32 v35, v163
	v_lshl_add_u64 v[172:173], s[2:3], 0, v[34:35]
	s_add_i32 s2, s29, 0xffffff45
	v_add_u32_e32 v2, s2, v181
	v_sub_u32_e32 v2, v2, v36
	v_mov_b32_e32 v188, 0
	v_mov_b32_e32 v167, v163
	v_lshl_add_u64 v[170:171], s[4:5], 0, v[34:35]
	s_mov_b32 s18, 2
	v_subrev_u32_e32 v195, s72, v2
	s_add_i32 s19, s72, 0x7f
	v_mov_b32_e32 v50, 0
	v_mov_b32_e32 v51, v188
	v_mov_b32_e32 v52, v188
	v_mov_b32_e32 v53, v188
	v_mov_b32_e32 v54, v188
	v_mov_b32_e32 v55, v188
	v_mov_b32_e32 v56, v188
	v_mov_b32_e32 v57, v188
	v_mov_b32_e32 v58, v188
	v_mov_b32_e32 v59, v188
	v_mov_b32_e32 v60, v188
	v_mov_b32_e32 v61, v188
	v_mov_b32_e32 v62, v188
	v_mov_b32_e32 v63, v188
	v_mov_b32_e32 v64, v188
	v_mov_b32_e32 v65, v188
	v_mov_b32_e32 v34, 0
	v_mov_b32_e32 v35, v188
	v_mov_b32_e32 v36, v188
	v_mov_b32_e32 v37, v188
	v_mov_b32_e32 v38, v188
	v_mov_b32_e32 v39, v188
	v_mov_b32_e32 v40, v188
	v_mov_b32_e32 v41, v188
	v_mov_b32_e32 v42, v188
	v_mov_b32_e32 v43, v188
	v_mov_b32_e32 v44, v188
	v_mov_b32_e32 v45, v188
	v_mov_b32_e32 v46, v188
	v_mov_b32_e32 v47, v188
	v_mov_b32_e32 v48, v188
	v_mov_b32_e32 v49, v188
	v_mov_b32_e32 v18, 0
	v_mov_b32_e32 v19, v188
	v_mov_b32_e32 v20, v188
	v_mov_b32_e32 v21, v188
	v_mov_b32_e32 v22, v188
	v_mov_b32_e32 v23, v188
	v_mov_b32_e32 v24, v188
	v_mov_b32_e32 v25, v188
	v_mov_b32_e32 v26, v188
	v_mov_b32_e32 v27, v188
	v_mov_b32_e32 v28, v188
	v_mov_b32_e32 v29, v188
	v_mov_b32_e32 v30, v188
	v_mov_b32_e32 v31, v188
	v_mov_b32_e32 v32, v188
	v_mov_b32_e32 v33, v188
	v_mov_b32_e32 v2, 0
	v_mov_b32_e32 v3, v188
	v_mov_b32_e32 v4, v188
	v_mov_b32_e32 v5, v188
	v_mov_b32_e32 v6, v188
	v_mov_b32_e32 v7, v188
	v_mov_b32_e32 v8, v188
	v_mov_b32_e32 v9, v188
	v_mov_b32_e32 v10, v188
	v_mov_b32_e32 v11, v188
	v_mov_b32_e32 v12, v188
	v_mov_b32_e32 v13, v188
	v_mov_b32_e32 v14, v188
	v_mov_b32_e32 v15, v188
	v_mov_b32_e32 v16, v188
	v_mov_b32_e32 v17, v188

.LBB0_793:
	v_max_f32_e32 v146, v83, v83
	v_max_f32_e32 v147, v82, v82
	v_max_f32_e32 v146, v147, v146
	v_max3_f32 v146, v146, v84, v85
	v_max3_f32 v146, v146, v86, v87
	v_max3_f32 v146, v146, v88, v89
	v_max3_f32 v146, v146, v90, v91
	v_max3_f32 v146, v146, v92, v93
	v_max3_f32 v146, v146, v94, v95
	v_max3_f32 v146, v146, v96, v97
	v_max3_f32 v146, v146, v66, v67
	v_max3_f32 v146, v146, v68, v69
	v_max3_f32 v146, v146, v70, v71
	v_max3_f32 v146, v146, v72, v73
	v_max3_f32 v146, v146, v74, v75
	v_max3_f32 v146, v146, v76, v77
	v_max3_f32 v146, v146, v78, v79
	v_max3_f32 v146, v146, v80, v81
	v_mov_b32_e32 v147, v146
	s_nop 1
	v_permlane32_swap_b32_e32 v146, v147
	v_max_f32_e32 v147, v147, v147
	v_max_f32_e32 v146, v146, v146
	v_max_f32_e32 v146, v146, v147
	v_max_f32_e32 v148, v194, v194
	v_sub_f32_e32 v147, v146, v194
	v_max_f32_e32 v146, v148, v146
	v_sub_f32_e32 v148, v194, v146
	v_mul_f32_e32 v148, 0x3e0293ee, v148
	v_mul_f32_e32 v147, 0x3db504f3, v147
	v_exp_f32_e32 v148, v148
	v_cmp_ge_f32_e32 vcc, s34, v147
	s_cmp_eq_u64 vcc, exec
	s_cselect_b64 s[2:3], -1, 0
	s_barrier
	s_waitcnt vmcnt(0)
	v_cndmask_b32_e64 v199, v148, 1.0, s[2:3]
	v_cmp_gt_f32_e32 vcc, 1.0, v199
	s_waitcnt vmcnt(3)
	ds_write_b128 v191, v[130:133]
	s_waitcnt vmcnt(2)
	ds_write_b128 v192, v[134:137]
	s_waitcnt vmcnt(1)
	ds_write_b128 v182, v[138:141] offset:32768
	s_waitcnt vmcnt(0)
	ds_write_b128 v182, v[142:145] offset:40960
	s_cbranch_vccz .LBB0_797
	s_and_saveexec_b64 s[4:5], s[0:1]
	ds_write_b32 v185, v199 offset:128
	s_or_b64 exec, exec, s[4:5]
	s_waitcnt lgkmcnt(0)
	ds_read_b128 v[148:151], v184 offset:224
	ds_read_b128 v[152:155], v184 offset:192
	ds_read_b128 v[156:159], v184 offset:160
	ds_read_b128 v[200:203], v184 offset:128
	s_waitcnt lgkmcnt(3)
	v_mul_f32 v64, v64, v150
	v_mul_f32 v65, v65, v151
	s_waitcnt lgkmcnt(2)
	v_mul_f32 v60, v60, v154
	v_mul_f32 v61, v61, v155
	s_waitcnt lgkmcnt(1)
	v_mul_f32 v56, v56, v158
	v_mul_f32 v57, v57, v159
	s_waitcnt lgkmcnt(0)
	v_mul_f32 v52, v52, v202
	v_mul_f32 v53, v53, v203
	v_mul_f32 v62, v62, v148
	v_mul_f32 v63, v63, v149
	v_mul_f32 v58, v58, v152
	v_mul_f32 v59, v59, v153
	v_mul_f32 v54, v54, v156
	v_mul_f32 v55, v55, v157
	v_mul_f32 v50, v50, v200
	v_mul_f32 v51, v51, v201
	v_mul_f32 v48, v48, v150
	v_mul_f32 v49, v49, v151
	v_mul_f32 v44, v44, v154
	v_mul_f32 v45, v45, v155
	v_mul_f32 v40, v40, v158
	v_mul_f32 v41, v41, v159
	v_mul_f32 v36, v36, v202
	v_mul_f32 v37, v37, v203
	v_mul_f32 v46, v46, v148
	v_mul_f32 v47, v47, v149
	v_mul_f32 v42, v42, v152
	v_mul_f32 v43, v43, v153
	v_mul_f32 v38, v38, v156
	v_mul_f32 v39, v39, v157
	v_mul_f32 v34, v34, v200
	v_mul_f32 v35, v35, v201
	v_mul_f32 v32, v32, v150
	v_mul_f32 v33, v33, v151
	v_mul_f32 v28, v28, v154
	v_mul_f32 v29, v29, v155
	v_mul_f32 v24, v24, v158
	v_mul_f32 v25, v25, v159
	v_mul_f32 v20, v20, v202
	v_mul_f32 v21, v21, v203
	v_mul_f32 v30, v30, v148
	v_mul_f32 v31, v31, v149
	v_mul_f32 v26, v26, v152
	v_mul_f32 v27, v27, v153
	v_mul_f32 v22, v22, v156
	v_mul_f32 v23, v23, v157
	v_mul_f32 v18, v18, v200
	v_mul_f32 v19, v19, v201
	v_mul_f32 v16, v16, v150
	v_mul_f32 v17, v17, v151
	v_mul_f32 v12, v12, v154
	v_mul_f32 v13, v13, v155
	v_mul_f32 v8, v8, v158
	v_mul_f32 v9, v9, v159
	v_mul_f32 v4, v4, v202
	v_mul_f32 v5, v5, v203
	v_mul_f32 v14, v14, v148
	v_mul_f32 v15, v15, v149
	v_mul_f32 v10, v10, v152
	v_mul_f32 v11, v11, v153
	v_mul_f32 v6, v6, v156
	v_mul_f32 v7, v7, v157
	v_mul_f32 v2, v2, v200
	v_mul_f32 v3, v3, v201

.LBB0_803:
	s_waitcnt vmcnt(3)
	v_max_f32_e32 v130, v174, v174
	v_max_f32_e32 v130, v130, v146
	v_sub_f32_e32 v131, v174, v130
	v_mul_f32_e32 v131, 0x3e0293ee, v131
	v_exp_f32_e32 v131, v131
	s_nop 0
	v_cndmask_b32_e64 v198, v131, 1.0, s[2:3]
	v_cmp_gt_f32_e32 vcc, 1.0, v198
	s_cbranch_vccz .LBB0_807
	s_and_saveexec_b64 s[4:5], s[0:1]
	ds_write_b32 v185, v198 offset:128
	s_or_b64 exec, exec, s[4:5]
	s_waitcnt lgkmcnt(0)
	s_waitcnt vmcnt(2)
	ds_read_b128 v[132:135], v184 offset:224
	s_waitcnt vmcnt(1)
	ds_read_b128 v[136:139], v184 offset:192
	s_waitcnt vmcnt(0)
	ds_read_b128 v[140:143], v184 offset:160
	ds_read_b128 v[144:147], v184 offset:128
	s_waitcnt lgkmcnt(3)
	v_mul_f32 v64, v64, v134
	v_mul_f32 v65, v65, v135
	s_waitcnt lgkmcnt(2)
	v_mul_f32 v60, v60, v138
	v_mul_f32 v61, v61, v139
	s_waitcnt lgkmcnt(1)
	v_mul_f32 v56, v56, v142
	v_mul_f32 v57, v57, v143
	s_waitcnt lgkmcnt(0)
	v_mul_f32 v52, v52, v146
	v_mul_f32 v53, v53, v147
	v_mul_f32 v62, v62, v132
	v_mul_f32 v63, v63, v133
	v_mul_f32 v58, v58, v136
	v_mul_f32 v59, v59, v137
	v_mul_f32 v54, v54, v140
	v_mul_f32 v55, v55, v141
	v_mul_f32 v50, v50, v144
	v_mul_f32 v51, v51, v145
	v_mul_f32 v48, v48, v134
	v_mul_f32 v49, v49, v135
	v_mul_f32 v44, v44, v138
	v_mul_f32 v45, v45, v139
	v_mul_f32 v40, v40, v142
	v_mul_f32 v41, v41, v143
	v_mul_f32 v36, v36, v146
	v_mul_f32 v37, v37, v147
	v_mul_f32 v46, v46, v132
	v_mul_f32 v47, v47, v133
	v_mul_f32 v42, v42, v136
	v_mul_f32 v43, v43, v137
	v_mul_f32 v38, v38, v140
	v_mul_f32 v39, v39, v141
	v_mul_f32 v34, v34, v144
	v_mul_f32 v35, v35, v145
	v_mul_f32 v32, v32, v134
	v_mul_f32 v33, v33, v135
	v_mul_f32 v28, v28, v138
	v_mul_f32 v29, v29, v139
	v_mul_f32 v24, v24, v142
	v_mul_f32 v25, v25, v143
	v_mul_f32 v20, v20, v146
	v_mul_f32 v21, v21, v147
	v_mul_f32 v30, v30, v132
	v_mul_f32 v31, v31, v133
	v_mul_f32 v26, v26, v136
	v_mul_f32 v27, v27, v137
	v_mul_f32 v22, v22, v140
	v_mul_f32 v23, v23, v141
	v_mul_f32 v18, v18, v144
	v_mul_f32 v19, v19, v145
	v_mul_f32 v16, v16, v134
	v_mul_f32 v17, v17, v135
	v_mul_f32 v12, v12, v138
	v_mul_f32 v13, v13, v139
	v_mul_f32 v8, v8, v142
	v_mul_f32 v9, v9, v143
	v_mul_f32 v4, v4, v146
	v_mul_f32 v5, v5, v147
	v_mul_f32 v14, v14, v132
	v_mul_f32 v15, v15, v133
	v_mul_f32 v10, v10, v136
	v_mul_f32 v11, v11, v137
	v_mul_f32 v6, v6, v140
	v_mul_f32 v7, v7, v141
	v_mul_f32 v2, v2, v144
	v_mul_f32 v3, v3, v145
.LBB0_807:
	v_cndmask_b32_e64 v194, v130, v174, s[2:3]
	v_mul_f32_e32 v130, 0xbe0293ee, v194
	v_mov_b32_e32 v131, v130
	v_fmamk_f32 v82, v82, 0x3e0293ee, v130
	v_fmamk_f32 v83, v83, 0x3e0293ee, v130
	v_fmamk_f32 v84, v84, 0x3e0293ee, v130
	v_fmamk_f32 v85, v85, 0x3e0293ee, v130
	v_fmamk_f32 v86, v86, 0x3e0293ee, v130
	v_fmamk_f32 v87, v87, 0x3e0293ee, v130
	v_fmamk_f32 v88, v88, 0x3e0293ee, v130
	v_fmamk_f32 v89, v89, 0x3e0293ee, v130
	v_fmamk_f32 v90, v90, 0x3e0293ee, v130
	v_fmamk_f32 v91, v91, 0x3e0293ee, v130
	v_fmamk_f32 v92, v92, 0x3e0293ee, v130
	v_fmamk_f32 v93, v93, 0x3e0293ee, v130
	v_fmamk_f32 v94, v94, 0x3e0293ee, v130
	v_fmamk_f32 v95, v95, 0x3e0293ee, v130
	v_fmamk_f32 v96, v96, 0x3e0293ee, v130
	v_fmac_f32_e32 v131, 0x3e0293ee, v97
	v_exp_f32_e32 v213, v82
	v_exp_f32_e32 v215, v83
	v_exp_f32_e32 v211, v84
	v_exp_f32_e32 v214, v85
	v_exp_f32_e32 v210, v86
	v_exp_f32_e32 v212, v87
	v_exp_f32_e32 v208, v88
	v_exp_f32_e32 v209, v89
	v_exp_f32_e32 v203, v90
	v_exp_f32_e32 v206, v91
	v_exp_f32_e32 v201, v92
	v_exp_f32_e32 v204, v93
	v_exp_f32_e32 v200, v94
	v_exp_f32_e32 v207, v95
	v_exp_f32_e32 v202, v96
	v_exp_f32_e32 v205, v131
	v_fma_f32 v174, v66, s8, v130
	v_fma_f32 v175, v67, s8, v130
	v_add_f32_e32 v66, v196, v197
	v_fmac_f32_e32 v66, v193, v188
	v_add_f32_e32 v188, v216, v217
	s_addk_i32 s19, 0x80
	s_add_i32 s18, s18, 2
	v_fma_f32 v148, v80, s8, v130
	v_fma_f32 v149, v81, s8, v130
	v_fma_f32 v150, v78, s8, v130
	v_fma_f32 v151, v79, s8, v130
	v_fma_f32 v152, v76, s8, v130
	v_fma_f32 v153, v77, s8, v130
	v_fma_f32 v154, v74, s8, v130
	v_fma_f32 v155, v75, s8, v130
	v_fma_f32 v156, v72, s8, v130
	v_fma_f32 v157, v73, s8, v130
	v_fma_f32 v158, v70, s8, v130
	v_fma_f32 v159, v71, s8, v130
	v_fma_f32 v160, v68, s8, v130
	v_fma_f32 v161, v69, s8, v130
	v_fmac_f32_e32 v188, v66, v199
	s_cmp_lt_i32 s18, s28
	v_add_u32_e32 v195, 0xffffff80, v195
	s_waitcnt lgkmcnt(0)
	s_barrier
	s_cbranch_scc0 .LBB0_810
	v_mov_b32_e32 v193, v198
	s_branch .LBB0_791

.LBB0_812:
	v_max_f32_e32 v149, v83, v83
	v_max_f32_e32 v150, v82, v82
	v_max_f32_e32 v149, v150, v149
	v_max3_f32 v149, v149, v84, v85
	v_max3_f32 v149, v149, v86, v87
	v_max3_f32 v149, v149, v88, v89
	v_max3_f32 v149, v149, v90, v91
	v_max3_f32 v149, v149, v92, v93
	v_max3_f32 v149, v149, v94, v95
	v_max3_f32 v149, v149, v96, v97
	v_max3_f32 v149, v149, v66, v67
	v_max3_f32 v149, v149, v68, v69
	v_max3_f32 v149, v149, v70, v71
	v_max3_f32 v149, v149, v72, v73
	v_max3_f32 v149, v149, v74, v75
	v_max3_f32 v149, v149, v76, v77
	v_max3_f32 v149, v149, v78, v79
	v_max3_f32 v149, v149, v80, v81
	v_mov_b32_e32 v150, v149
	s_nop 1
	v_permlane32_swap_b32_e32 v149, v150
	v_max_f32_e32 v150, v150, v150
	v_max_f32_e32 v149, v149, v149
	v_max_f32_e32 v149, v149, v150
	v_max_f32_e32 v151, v194, v194
	v_sub_f32_e32 v150, v149, v194
	v_max_f32_e32 v149, v151, v149
	v_sub_f32_e32 v151, v194, v149
	v_mul_f32_e32 v151, 0x3e0293ee, v151
	v_mul_f32_e32 v150, 0x3db504f3, v150
	v_exp_f32_e32 v151, v151
	v_cmp_ge_f32_e32 vcc, s34, v150
	s_cmp_eq_u64 vcc, exec
	s_cselect_b64 s[0:1], -1, 0
	v_cndmask_b32_e64 v150, v151, 1.0, s[0:1]
	v_cmp_gt_f32_e32 vcc, 1.0, v150
	s_barrier
	s_cbranch_vccz .LBB0_816
	v_cmp_gt_u32_e32 vcc, 32, v183
	s_and_saveexec_b64 s[4:5], vcc
	ds_write_b32 v185, v150 offset:128
	s_or_b64 exec, exec, s[4:5]
	s_waitcnt lgkmcnt(0)
	ds_read_b128 v[152:155], v184 offset:224
	ds_read_b128 v[156:159], v184 offset:192
	ds_read_b128 v[164:167], v184 offset:160
	ds_read_b128 v[168:171], v184 offset:128
	s_waitcnt lgkmcnt(3)
	v_mul_f32 v64, v64, v154
	v_mul_f32 v65, v65, v155
	s_waitcnt lgkmcnt(2)
	v_mul_f32 v60, v60, v158
	v_mul_f32 v61, v61, v159
	s_waitcnt lgkmcnt(1)
	v_mul_f32 v56, v56, v166
	v_mul_f32 v57, v57, v167
	s_waitcnt lgkmcnt(0)
	v_mul_f32 v52, v52, v170
	v_mul_f32 v53, v53, v171
	v_mul_f32 v62, v62, v152
	v_mul_f32 v63, v63, v153
	v_mul_f32 v58, v58, v156
	v_mul_f32 v59, v59, v157
	v_mul_f32 v54, v54, v164
	v_mul_f32 v55, v55, v165
	v_mul_f32 v50, v50, v168
	v_mul_f32 v51, v51, v169
	v_mul_f32 v48, v48, v154
	v_mul_f32 v49, v49, v155
	v_mul_f32 v44, v44, v158
	v_mul_f32 v45, v45, v159
	v_mul_f32 v40, v40, v166
	v_mul_f32 v41, v41, v167
	v_mul_f32 v36, v36, v170
	v_mul_f32 v37, v37, v171
	v_mul_f32 v46, v46, v152
	v_mul_f32 v47, v47, v153
	v_mul_f32 v42, v42, v156
	v_mul_f32 v43, v43, v157
	v_mul_f32 v38, v38, v164
	v_mul_f32 v39, v39, v165
	v_mul_f32 v34, v34, v168
	v_mul_f32 v35, v35, v169
	v_mul_f32 v32, v32, v154
	v_mul_f32 v33, v33, v155
	v_mul_f32 v28, v28, v158
	v_mul_f32 v29, v29, v159
	v_mul_f32 v24, v24, v166
	v_mul_f32 v25, v25, v167
	v_mul_f32 v20, v20, v170
	v_mul_f32 v21, v21, v171
	v_mul_f32 v30, v30, v152
	v_mul_f32 v31, v31, v153
	v_mul_f32 v26, v26, v156
	v_mul_f32 v27, v27, v157
	v_mul_f32 v22, v22, v164
	v_mul_f32 v23, v23, v165
	v_mul_f32 v18, v18, v168
	v_mul_f32 v19, v19, v169
	v_mul_f32 v16, v16, v154
	v_mul_f32 v17, v17, v155
	v_mul_f32 v12, v12, v158
	v_mul_f32 v13, v13, v159
	v_mul_f32 v8, v8, v166
	v_mul_f32 v9, v9, v167
	v_mul_f32 v4, v4, v170
	v_mul_f32 v5, v5, v171
	v_mul_f32 v14, v14, v152
	v_mul_f32 v15, v15, v153
	v_mul_f32 v10, v10, v156
	v_mul_f32 v11, v11, v157
	v_mul_f32 v6, v6, v164
	v_mul_f32 v7, v7, v165
	v_mul_f32 v2, v2, v168
	v_mul_f32 v3, v3, v169

.LBB0_952:
	v_max_f32_e32 v169, v83, v83
	v_max_f32_e32 v174, v82, v82
	v_max_f32_e32 v169, v174, v169
	v_max3_f32 v169, v169, v84, v85
	v_max3_f32 v169, v169, v86, v87
	v_max3_f32 v169, v169, v88, v89
	v_max3_f32 v169, v169, v90, v91
	v_max3_f32 v169, v169, v92, v93
	v_max3_f32 v169, v169, v94, v95
	v_max3_f32 v169, v169, v96, v97
	v_max3_f32 v169, v169, v66, v67
	v_max3_f32 v169, v169, v68, v69
	v_max3_f32 v169, v169, v70, v71
	v_max3_f32 v169, v169, v72, v73
	v_max3_f32 v169, v169, v74, v75
	v_max3_f32 v169, v169, v76, v77
	v_max3_f32 v169, v169, v78, v79
	v_max3_f32 v169, v169, v80, v81
	v_mov_b32_e32 v174, v169
	s_nop 1
	v_permlane32_swap_b32_e32 v169, v174
	v_max_f32_e32 v174, v174, v174
	v_max_f32_e32 v169, v169, v169
	v_max_f32_e32 v169, v169, v174
	v_sub_f32_e32 v174, v169, v173
	v_mul_f32_e32 v175, 0x3db504f3, v174
	v_max_f32_e32 v174, v173, v173
	v_max_f32_e32 v174, v174, v169
	s_and_b32 s2, s4, 0x3fffffc0
	v_sub_f32_e32 v169, v173, v174
	s_lshl_b32 s2, s2, 2
	v_mul_f32_e32 v169, 0x3e0293ee, v169
	s_add_i32 s66, s2, 0
	v_exp_f32_e32 v169, v169
	s_add_i32 s66, s66, 0x10000
	v_cmp_ge_f32_e32 vcc, s34, v175
	s_cmp_eq_u64 vcc, exec
	s_cselect_b64 s[4:5], -1, 0
	s_barrier
	s_waitcnt vmcnt(0)
	v_cndmask_b32_e64 v169, v169, 1.0, s[4:5]
	v_cmp_gt_u32_e64 s[2:3], 32, v165
	v_lshl_add_u32 v165, v156, 2, s66
	v_cmp_gt_f32_e32 vcc, 1.0, v169
	s_waitcnt vmcnt(3)
	ds_write_b128 v170, v[130:133]
	s_waitcnt vmcnt(2)
	ds_write_b128 v171, v[134:137]
	s_waitcnt vmcnt(1)
	ds_write_b128 v159, v[138:141] offset:32768
	s_waitcnt vmcnt(0)
	ds_write_b128 v159, v[142:145] offset:40960
	s_cbranch_vccz .LBB0_956
	s_and_saveexec_b64 s[18:19], s[2:3]
	ds_write_b32 v165, v169 offset:128
	s_or_b64 exec, exec, s[18:19]
	s_waitcnt lgkmcnt(0)
	v_lshl_add_u32 v142, v157, 2, s66
	ds_read_b128 v[130:133], v142 offset:224
	ds_read_b128 v[134:137], v142 offset:192
	ds_read_b128 v[138:141], v142 offset:160
	ds_read_b128 v[142:145], v142 offset:128
	s_waitcnt lgkmcnt(3)
	v_mul_f32 v16, v16, v132
	v_mul_f32 v17, v17, v133
	s_waitcnt lgkmcnt(2)
	v_mul_f32 v12, v12, v136
	v_mul_f32 v13, v13, v137
	s_waitcnt lgkmcnt(1)
	v_mul_f32 v8, v8, v140
	v_mul_f32 v9, v9, v141
	s_waitcnt lgkmcnt(0)
	v_mul_f32 v4, v4, v144
	v_mul_f32 v5, v5, v145
	v_mul_f32 v14, v14, v130
	v_mul_f32 v15, v15, v131
	v_mul_f32 v10, v10, v134
	v_mul_f32 v11, v11, v135
	v_mul_f32 v6, v6, v138
	v_mul_f32 v7, v7, v139
	v_mul_f32 v2, v2, v142
	v_mul_f32 v3, v3, v143
	v_mul_f32 v32, v32, v132
	v_mul_f32 v33, v33, v133
	v_mul_f32 v28, v28, v136
	v_mul_f32 v29, v29, v137
	v_mul_f32 v24, v24, v140
	v_mul_f32 v25, v25, v141
	v_mul_f32 v20, v20, v144
	v_mul_f32 v21, v21, v145
	v_mul_f32 v30, v30, v130
	v_mul_f32 v31, v31, v131
	v_mul_f32 v26, v26, v134
	v_mul_f32 v27, v27, v135
	v_mul_f32 v22, v22, v138
	v_mul_f32 v23, v23, v139
	v_mul_f32 v18, v18, v142
	v_mul_f32 v19, v19, v143
	v_mul_f32 v48, v48, v132
	v_mul_f32 v49, v49, v133
	v_mul_f32 v44, v44, v136
	v_mul_f32 v45, v45, v137
	v_mul_f32 v40, v40, v140
	v_mul_f32 v41, v41, v141
	v_mul_f32 v36, v36, v144
	v_mul_f32 v37, v37, v145
	v_mul_f32 v46, v46, v130
	v_mul_f32 v47, v47, v131
	v_mul_f32 v42, v42, v134
	v_mul_f32 v43, v43, v135
	v_mul_f32 v38, v38, v138
	v_mul_f32 v39, v39, v139
	v_mul_f32 v34, v34, v142
	v_mul_f32 v35, v35, v143
	v_mul_f32 v64, v64, v132
	v_mul_f32 v65, v65, v133
	v_mul_f32 v60, v60, v136
	v_mul_f32 v61, v61, v137
	v_mul_f32 v56, v56, v140
	v_mul_f32 v57, v57, v141
	v_mul_f32 v52, v52, v144
	v_mul_f32 v53, v53, v145
	v_mul_f32 v62, v62, v130
	v_mul_f32 v63, v63, v131
	v_mul_f32 v58, v58, v134
	v_mul_f32 v59, v59, v135
	v_mul_f32 v54, v54, v138
	v_mul_f32 v55, v55, v139
	v_mul_f32 v50, v50, v142
	v_mul_f32 v51, v51, v143

.LBB0_958:
	v_max_f32_e32 v150, v83, v83
	v_max_f32_e32 v151, v82, v82
	v_max_f32_e32 v150, v151, v150
	v_max3_f32 v150, v150, v84, v85
	v_max3_f32 v150, v150, v86, v87
	v_max3_f32 v150, v150, v88, v89
	v_max3_f32 v150, v150, v90, v91
	v_max3_f32 v150, v150, v92, v93
	v_max3_f32 v150, v150, v94, v95
	v_max3_f32 v150, v150, v96, v97
	v_max3_f32 v150, v150, v66, v67
	v_max3_f32 v150, v150, v68, v69
	v_max3_f32 v150, v150, v70, v71
	v_max3_f32 v150, v150, v72, v73
	v_max3_f32 v150, v150, v74, v75
	v_max3_f32 v150, v150, v76, v77
	v_max3_f32 v150, v150, v78, v79
	v_max3_f32 v150, v150, v80, v81
	v_mov_b32_e32 v151, v150
	s_nop 1
	v_permlane32_swap_b32_e32 v150, v151
	v_max_f32_e32 v151, v151, v151
	v_max_f32_e32 v150, v150, v150
	v_max_f32_e32 v150, v150, v151
	v_sub_f32_e32 v151, v150, v175
	v_mul_f32_e32 v152, 0x3db504f3, v151
	v_max_f32_e32 v151, v175, v175
	v_max_f32_e32 v151, v151, v150
	v_sub_f32_e32 v150, v175, v151
	v_mul_f32_e32 v150, 0x3e0293ee, v150
	v_exp_f32_e32 v150, v150
	v_cmp_ge_f32_e32 vcc, s34, v152
	s_cmp_eq_u64 vcc, exec
	s_cselect_b64 s[4:5], -1, 0
	s_barrier
	s_waitcnt vmcnt(0)
	v_cndmask_b32_e64 v150, v150, 1.0, s[4:5]
	v_cmp_gt_f32_e32 vcc, 1.0, v150
	s_waitcnt vmcnt(3)
	ds_write_b128 v170, v[130:133] offset:16384
	s_waitcnt vmcnt(2)
	ds_write_b128 v171, v[134:137] offset:16384
	s_waitcnt vmcnt(1)
	ds_write_b128 v159, v[138:141] offset:49152
	s_waitcnt vmcnt(0)
	ds_write_b128 v159, v[142:145] offset:57344
	s_cbranch_vccz .LBB0_962
	s_and_saveexec_b64 s[18:19], s[2:3]
	ds_write_b32 v165, v150 offset:128
	s_or_b64 exec, exec, s[18:19]
	s_waitcnt lgkmcnt(0)
	v_lshl_add_u32 v142, v157, 2, s66
	ds_read_b128 v[130:133], v142 offset:224
	ds_read_b128 v[134:137], v142 offset:192
	ds_read_b128 v[138:141], v142 offset:160
	ds_read_b128 v[142:145], v142 offset:128
	s_waitcnt lgkmcnt(3)
	v_mul_f32 v16, v16, v132
	v_mul_f32 v17, v17, v133
	s_waitcnt lgkmcnt(2)
	v_mul_f32 v12, v12, v136
	v_mul_f32 v13, v13, v137
	s_waitcnt lgkmcnt(1)
	v_mul_f32 v8, v8, v140
	v_mul_f32 v9, v9, v141
	s_waitcnt lgkmcnt(0)
	v_mul_f32 v4, v4, v144
	v_mul_f32 v5, v5, v145
	v_mul_f32 v14, v14, v130
	v_mul_f32 v15, v15, v131
	v_mul_f32 v10, v10, v134
	v_mul_f32 v11, v11, v135
	v_mul_f32 v6, v6, v138
	v_mul_f32 v7, v7, v139
	v_mul_f32 v2, v2, v142
	v_mul_f32 v3, v3, v143
	v_mul_f32 v32, v32, v132
	v_mul_f32 v33, v33, v133
	v_mul_f32 v28, v28, v136
	v_mul_f32 v29, v29, v137
	v_mul_f32 v24, v24, v140
	v_mul_f32 v25, v25, v141
	v_mul_f32 v20, v20, v144
	v_mul_f32 v21, v21, v145
	v_mul_f32 v30, v30, v130
	v_mul_f32 v31, v31, v131
	v_mul_f32 v26, v26, v134
	v_mul_f32 v27, v27, v135
	v_mul_f32 v22, v22, v138
	v_mul_f32 v23, v23, v139
	v_mul_f32 v18, v18, v142
	v_mul_f32 v19, v19, v143
	v_mul_f32 v48, v48, v132
	v_mul_f32 v49, v49, v133
	v_mul_f32 v44, v44, v136
	v_mul_f32 v45, v45, v137
	v_mul_f32 v40, v40, v140
	v_mul_f32 v41, v41, v141
	v_mul_f32 v36, v36, v144
	v_mul_f32 v37, v37, v145
	v_mul_f32 v46, v46, v130
	v_mul_f32 v47, v47, v131
	v_mul_f32 v42, v42, v134
	v_mul_f32 v43, v43, v135
	v_mul_f32 v38, v38, v138
	v_mul_f32 v39, v39, v139
	v_mul_f32 v34, v34, v142
	v_mul_f32 v35, v35, v143
	v_mul_f32 v64, v64, v132
	v_mul_f32 v65, v65, v133
	v_mul_f32 v60, v60, v136
	v_mul_f32 v61, v61, v137
	v_mul_f32 v56, v56, v140
	v_mul_f32 v57, v57, v141
	v_mul_f32 v52, v52, v144
	v_mul_f32 v53, v53, v145
	v_mul_f32 v62, v62, v130
	v_mul_f32 v63, v63, v131
	v_mul_f32 v58, v58, v134
	v_mul_f32 v59, v59, v135
	v_mul_f32 v54, v54, v138
	v_mul_f32 v55, v55, v139
	v_mul_f32 v50, v50, v142
	v_mul_f32 v51, v51, v143

.LBB0_964:
	v_max_f32_e32 v108, v83, v83
	v_max_f32_e32 v109, v82, v82
	v_max_f32_e32 v108, v109, v108
	v_max3_f32 v108, v108, v84, v85
	v_max3_f32 v108, v108, v86, v87
	v_max3_f32 v108, v108, v88, v89
	v_max3_f32 v108, v108, v90, v91
	v_max3_f32 v108, v108, v92, v93
	v_max3_f32 v108, v108, v94, v95
	v_max3_f32 v108, v108, v96, v97
	v_max3_f32 v108, v108, v66, v67
	v_max3_f32 v108, v108, v68, v69
	v_max3_f32 v108, v108, v70, v71
	v_max3_f32 v108, v108, v72, v73
	v_max3_f32 v108, v108, v74, v75
	v_max3_f32 v108, v108, v76, v77
	v_max3_f32 v108, v108, v78, v79
	v_max3_f32 v108, v108, v80, v81
	v_mov_b32_e32 v109, v108
	s_nop 1
	v_permlane32_swap_b32_e32 v108, v109
	v_max_f32_e32 v109, v109, v109
	v_max_f32_e32 v108, v108, v108
	v_max_f32_e32 v108, v108, v109
	v_max_f32_e32 v110, v130, v130
	v_sub_f32_e32 v109, v108, v130
	v_max_f32_e32 v108, v110, v108
	v_sub_f32_e32 v110, v130, v108
	v_mul_f32_e32 v110, 0x3e0293ee, v110
	v_mul_f32_e32 v109, 0x3db504f3, v109
	v_exp_f32_e32 v110, v110
	v_cmp_ge_f32_e32 vcc, s34, v109
	s_cmp_eq_u64 vcc, exec
	s_cselect_b64 s[4:5], -1, 0
	v_cndmask_b32_e64 v109, v110, 1.0, s[4:5]
	v_cmp_gt_f32_e32 vcc, 1.0, v109
	s_barrier
	s_cbranch_vccz .LBB0_968
	s_and_saveexec_b64 s[18:19], s[2:3]
	ds_write_b32 v165, v109 offset:128
	s_or_b64 exec, exec, s[18:19]
	s_waitcnt lgkmcnt(0)
	v_lshl_add_u32 v122, v157, 2, s66
	ds_read_b128 v[110:113], v122 offset:224
	ds_read_b128 v[114:117], v122 offset:192
	ds_read_b128 v[118:121], v122 offset:160
	ds_read_b128 v[122:125], v122 offset:128
	s_waitcnt lgkmcnt(3)
	v_mul_f32 v16, v16, v112
	v_mul_f32 v17, v17, v113
	s_waitcnt lgkmcnt(2)
	v_mul_f32 v12, v12, v116
	v_mul_f32 v13, v13, v117
	s_waitcnt lgkmcnt(1)
	v_mul_f32 v8, v8, v120
	v_mul_f32 v9, v9, v121
	s_waitcnt lgkmcnt(0)
	v_mul_f32 v4, v4, v124
	v_mul_f32 v5, v5, v125
	v_mul_f32 v14, v14, v110
	v_mul_f32 v15, v15, v111
	v_mul_f32 v10, v10, v114
	v_mul_f32 v11, v11, v115
	v_mul_f32 v6, v6, v118
	v_mul_f32 v7, v7, v119
	v_mul_f32 v2, v2, v122
	v_mul_f32 v3, v3, v123
	v_mul_f32 v32, v32, v112
	v_mul_f32 v33, v33, v113
	v_mul_f32 v28, v28, v116
	v_mul_f32 v29, v29, v117
	v_mul_f32 v24, v24, v120
	v_mul_f32 v25, v25, v121
	v_mul_f32 v20, v20, v124
	v_mul_f32 v21, v21, v125
	v_mul_f32 v30, v30, v110
	v_mul_f32 v31, v31, v111
	v_mul_f32 v26, v26, v114
	v_mul_f32 v27, v27, v115
	v_mul_f32 v22, v22, v118
	v_mul_f32 v23, v23, v119
	v_mul_f32 v18, v18, v122
	v_mul_f32 v19, v19, v123
	v_mul_f32 v48, v48, v112
	v_mul_f32 v49, v49, v113
	v_mul_f32 v44, v44, v116
	v_mul_f32 v45, v45, v117
	v_mul_f32 v40, v40, v120
	v_mul_f32 v41, v41, v121
	v_mul_f32 v36, v36, v124
	v_mul_f32 v37, v37, v125
	v_mul_f32 v46, v46, v110
	v_mul_f32 v47, v47, v111
	v_mul_f32 v42, v42, v114
	v_mul_f32 v43, v43, v115
	v_mul_f32 v38, v38, v118
	v_mul_f32 v39, v39, v119
	v_mul_f32 v34, v34, v122
	v_mul_f32 v35, v35, v123
	v_mul_f32 v64, v64, v112
	v_mul_f32 v65, v65, v113
	v_mul_f32 v60, v60, v116
	v_mul_f32 v61, v61, v117
	v_mul_f32 v56, v56, v120
	v_mul_f32 v57, v57, v121
	v_mul_f32 v52, v52, v124
	v_mul_f32 v53, v53, v125
	v_mul_f32 v62, v62, v110
	v_mul_f32 v63, v63, v111
	v_mul_f32 v58, v58, v114
	v_mul_f32 v59, v59, v115
	v_mul_f32 v54, v54, v118
	v_mul_f32 v55, v55, v119
	v_mul_f32 v50, v50, v122
	v_mul_f32 v51, v51, v123
